# attention: V^T LDS tile row stride 264->268 bf16 (OST/SSQ moved up 512 B) so the PV-stage ds_read2_b64 fragment reads are bank-conflict-free
# baseline (speedup 1.0000x reference)
.LBB0_294:
	s_cmp_lt_i32 s80, 4
	s_cselect_b64 s[0:1], -1, 0
	s_cmp_gt_i32 s81, 3
	s_cselect_b64 s[4:5], -1, 0
	s_and_b64 s[0:1], s[0:1], s[4:5]
	s_andn2_b64 vcc, exec, s[0:1]
	s_cbranch_vccnz .LBB0_381
	v_lshrrev_b32_e32 v0, 5, v193
	s_cmpk_gt_i32 s2, 0x2ff
	v_and_b32_e32 v124, 31, v144
	v_mov_b32_e32 v127, 0
	v_lshlrev_b32_e32 v141, 3, v0
	v_lshlrev_b32_e32 v129, 2, v0
	s_cbranch_scc1 .LBB0_324
	v_and_b32_e32 v1, 7, v144
	v_lshl_add_u32 v3, v1, 4, 0
	v_lshlrev_b32_e32 v2, 3, v1
	v_add_u32_e32 v1, 0x200, v144
	v_lshrrev_b32_e32 v130, 3, v1
	v_or_b32_e32 v8, 0x400, v144
	v_lshrrev_b32_e32 v1, 5, v1
	s_add_u32 s50, s62, 0xc000000
	v_add_u32_e32 v10, 0x600, v144
	v_and_b32_e32 v6, 56, v1
	v_lshrrev_b32_e32 v1, 5, v8
	s_addc_u32 s51, s63, 0
	v_lshrrev_b32_e32 v132, 3, v8
	v_and_b32_e32 v8, 56, v1
	v_lshrrev_b32_e32 v1, 5, v10
	s_mul_i32 s6, s3, 0x1200
	v_lshrrev_b32_e32 v134, 3, v10
	v_and_b32_e32 v10, 0x78, v1
	s_add_u32 s93, s62, 0x1d00000
	v_lshlrev_b32_e32 v1, 3, v144
	s_addc_u32 s94, s63, 0
	s_add_i32 s6, s6, 0
	v_and_b32_e32 v12, 56, v1
	s_add_i32 s8, s6, 0x11600
	v_lshlrev_b32_e32 v126, 2, v12
	s_movk_i32 s92, 0x90
	s_waitcnt lgkmcnt(0)
	v_lshl_add_u64 v[138:139], s[12:13], 0, v[126:127]
	v_lshlrev_b32_e32 v18, 4, v0
	v_mov_b32_e32 v0, s8
	v_lshlrev_b32_e32 v126, 1, v12
	v_mad_u32_u24 v19, v124, s92, v0
	v_add_u32_e32 v20, s8, v126
	v_lshl_add_u64 v[0:1], s[62:63], 0, v[126:127]
	s_mov_b64 s[8:9], 0x4000000
	v_lshl_add_u64 v[142:143], v[0:1], 0, s[8:9]
	v_or_b32_e32 v0, 2, v129
	v_cmp_gt_u32_e64 s[12:13], v0, v124
	v_or_b32_e32 v0, 3, v129
	v_cmp_gt_u32_e64 s[14:15], v0, v124
	v_or_b32_e32 v0, 8, v129
	v_cmp_gt_u32_e64 s[16:17], v0, v124
	v_or_b32_e32 v0, 9, v129
	v_cmp_gt_u32_e64 s[18:19], v0, v124
	v_or_b32_e32 v0, 10, v129
	v_cmp_gt_u32_e64 s[20:21], v0, v124
	v_or_b32_e32 v0, 11, v129
	v_cmp_gt_u32_e64 s[22:23], v0, v124
	v_or_b32_e32 v0, 16, v129
	v_cmp_gt_u32_e64 s[24:25], v0, v124
	v_or_b32_e32 v0, 17, v129
	v_cmp_gt_u32_e64 s[26:27], v0, v124
	v_or_b32_e32 v0, 18, v129
	v_cmp_gt_u32_e64 s[28:29], v0, v124
	v_or_b32_e32 v0, 19, v129
	v_cmp_gt_u32_e64 s[30:31], v0, v124
	v_or_b32_e32 v0, 24, v129
	v_cmp_gt_u32_e64 s[34:35], v0, v124
	v_or_b32_e32 v0, 25, v129
	v_cmp_gt_u32_e64 s[36:37], v0, v124
	v_or_b32_e32 v0, 26, v129
	v_cmp_gt_u32_e64 s[38:39], v0, v124
	v_or_b32_e32 v0, 27, v129
	v_cmp_gt_u32_e64 s[40:41], v0, v124
	v_or_b32_e32 v0, 32, v193
	v_mul_u32_u24_e32 v22, 0x218, v0
	v_mbcnt_lo_u32_b32 v0, -1, 0
	v_mbcnt_hi_u32_b32 v0, -1, v0
	v_and_b32_e32 v24, 64, v0
	v_xor_b32_e32 v1, 32, v0
	v_add_u32_e32 v24, 64, v24
	v_cmp_lt_i32_e32 vcc, v1, v24
	s_mov_b64 s[56:57], 0xc048040
	v_lshrrev_b32_e32 v4, 5, v144
	v_cndmask_b32_e32 v0, v0, v1, vcc
	v_lshlrev_b32_e32 v171, 2, v0
	v_lshrrev_b32_e32 v0, 1, v144
	v_and_b32_e32 v126, 16, v0
	v_lshl_add_u64 v[0:1], s[62:63], 0, v[126:127]
	v_lshl_add_u64 v[148:149], v[0:1], 0, s[56:57]
	v_mul_u32_u24_e32 v0, 0x90, v124
	v_add3_u32 v0, v0, v18, 0
	v_add_u32_e32 v172, 0x1200, v0
	v_add_u32_e32 v0, v22, v141
	v_mul_u32_u24_e32 v21, 0x218, v124
	v_add_u32_e32 v0, 0, v0
	v_lshrrev_b32_e32 v128, 3, v144
	v_and_b32_e32 v136, 0xff, v144
	v_and_b32_e32 v4, 24, v4
	v_lshrrev_b32_e32 v145, 3, v193
	s_lshl_b32 s66, s3, 9
	s_add_i32 s67, 0, 0x1a600
	v_add_u32_e32 v174, 0x9000, v0
	v_add_u32_e32 v0, v21, v141
	v_mul_u32_u24_e32 v5, 0x90, v128
	s_movk_i32 s0, 0x1ff
	v_mul_u32_u24_e32 v7, 0x90, v130
	v_mul_u32_u24_e32 v9, 0x90, v132
	v_mul_u32_u24_e32 v11, 0x90, v134
	s_movk_i32 s4, 0x7f
	v_lshl_add_u32 v13, v136, 1, 0
	v_mul_u32_u24_e32 v14, 0x218, v4
	v_mul_u32_u24_e32 v15, 0x218, v6
	v_mul_u32_u24_e32 v16, 0x218, v8
	v_mul_u32_u24_e32 v17, 0x218, v10
	v_mul_u32_u24_e32 v23, 0x90, v145
	s_movk_i32 s42, 0x80
	v_lshl_add_u32 v170, v144, 2, s67
	s_add_i32 s67, s67, s66
	v_add_u32_e32 v0, 0, v0
	v_mov_b32_e32 v125, v127
	v_cmp_lt_u32_e64 s[0:1], s0, v144
	v_mov_b32_e32 v131, v127
	v_mov_b32_e32 v133, v127
	v_mov_b32_e32 v135, v127
	v_cmp_lt_u32_e64 s[4:5], s4, v136
	v_mov_b32_e32 v137, v127
	v_add_u32_e32 v140, 0, v18
	v_cmp_gt_u32_e64 s[6:7], 32, v193
	v_cmp_gt_u32_e64 s[8:9], v129, v124
	v_cmp_lt_u32_e64 s[10:11], v129, v124
	v_or_b32_e32 v147, 8, v145
	v_or_b32_e32 v168, 16, v145
	v_or_b32_e32 v169, 24, v145
	v_cmp_gt_u32_e64 s[42:43], s42, v144
	v_lshl_add_u32 v173, v193, 2, s67
	v_add_u32_e32 v175, 0x9000, v0
	s_movk_i32 s95, 0x2400
	v_add_u32_e32 v176, v3, v7
	v_lshlrev_b32_e32 v150, 1, v2
	v_add_u32_e32 v177, v3, v9
	v_add_u32_e32 v178, v3, v11
	v_lshlrev_b32_e32 v152, 1, v4
	v_add_u32_e32 v179, v13, v14
	v_lshlrev_b32_e32 v154, 1, v6
	v_add_u32_e32 v180, v13, v15
	v_lshlrev_b32_e32 v156, 1, v8
	v_add_u32_e32 v181, v13, v16
	v_lshlrev_b32_e32 v158, 1, v10
	v_add_u32_e32 v182, v13, v17
	v_lshlrev_b32_e32 v160, 1, v12
	s_movk_i32 s96, 0x1000
	s_mov_b32 s97, 0xf149f2ca
	v_add_u32_e32 v183, v19, v141
	v_add_u32_e32 v184, v20, v23
	s_mov_b64 s[56:57], 0x48000
	v_lshlrev_b32_e32 v185, 2, v144
	v_add_u32_e32 v186, v3, v5
	v_mov_b32_e32 v194, v127
	v_mov_b32_e32 v195, v127
	v_mov_b32_e32 v196, v127
	v_mov_b32_e32 v197, v127
	v_mov_b32_e32 v187, 0x2400
	v_mov_b32_e32 v188, 0xf149f2ca
	s_mov_b32 s98, s2
	s_branch .LBB0_298

.Lattn_stage_k23:
	global_load_dwordx4 v[12:15], v252, s[86:87] offset:3072
	global_load_dwordx4 v[230:233], v253, s[86:87] offset:3072
	s_mov_b32 s69, 0
	s_lshl_b32 s70, s68, 3
	s_add_i32 s76, s70, s3
	v_or_b32_e32 v2, s66, v124
	v_mov_b64_e32 v[0:1], s[50:51]
	s_lshl_b32 s84, s76, 6
	v_mad_u64_u32 v[0:1], s[70:71], v2, s95, v[0:1]
	s_ashr_i32 s85, s84, 31
	v_mad_i32_i24 v1, s67, v187, v1
	s_lshl_b64 s[70:71], s[84:85], 1
	s_ashr_i32 s77, s76, 31
	v_lshl_add_u64 v[0:1], v[0:1], 0, s[70:71]
	v_lshlrev_b32_e32 v126, 1, v141
	s_lshl_b64 s[76:77], s[76:77], 2
	v_lshl_add_u64 v[0:1], v[0:1], 0, v[126:127]
	s_add_u32 s76, s78, s76
	global_load_dwordx4 v[48:51], v[0:1], off nt
	global_load_dwordx4 v[108:111], v[0:1], off offset:32 nt
	global_load_dwordx4 v[104:107], v[0:1], off offset:64 nt
	global_load_dwordx4 v[120:123], v[0:1], off offset:96 nt
	s_addc_u32 s77, s79, s77
	global_load_dword v16, v127, s[76:77]
	v_lshl_add_u64 v[0:1], s[84:85], 2, v[138:139]
	global_load_dwordx4 v[80:83], v[0:1], off
	global_load_dwordx4 v[84:87], v[0:1], off offset:16
	s_waitcnt vmcnt(8)
	ds_write_b128 v186, v[4:7]
	ds_write_b128 v176, v[8:11]
	ds_write_b128 v177, v[12:15]
	ds_write_b16 v179, v234 offset:36864
	ds_write_b16_d16_hi v179, v234 offset:37400
	ds_write_b16 v179, v235 offset:37936
	ds_write_b16_d16_hi v179, v235 offset:38472
	ds_write_b16 v179, v236 offset:39008
	ds_write_b16_d16_hi v179, v236 offset:39544
	ds_write_b16 v179, v237 offset:40080
	ds_write_b16_d16_hi v179, v237 offset:40616
	ds_write_b16 v180, v238 offset:36864
	ds_write_b16_d16_hi v180, v238 offset:37400
	ds_write_b16 v180, v239 offset:37936
	ds_write_b16_d16_hi v180, v239 offset:38472
	ds_write_b16 v180, v240 offset:39008
	ds_write_b16_d16_hi v180, v240 offset:39544
	ds_write_b16 v180, v241 offset:40080
	ds_write_b16_d16_hi v180, v241 offset:40616
	ds_write_b16 v181, v242 offset:36864
	ds_write_b16_d16_hi v181, v242 offset:37400
	ds_write_b16 v181, v243 offset:37936
	ds_write_b16_d16_hi v181, v243 offset:38472
	ds_write_b16 v181, v244 offset:39008
	ds_write_b16_d16_hi v181, v244 offset:39544
	ds_write_b16 v181, v245 offset:40080
	ds_write_b16_d16_hi v181, v245 offset:40616
	ds_write_b16 v182, v246 offset:36864
	ds_write_b16_d16_hi v182, v246 offset:37400
	ds_write_b16 v182, v247 offset:37936
	ds_write_b16_d16_hi v182, v247 offset:38472
	ds_write_b16 v182, v248 offset:39008
	ds_write_b16_d16_hi v182, v248 offset:39544
	ds_write_b16 v182, v249 offset:40080
	ds_write_b16_d16_hi v182, v249 offset:40616
	s_waitcnt vmcnt(7)
	ds_write_b128 v178, v[230:233]
	s_waitcnt lgkmcnt(0)
	s_barrier
	s_mul_i32 s85, s72, 0x9000000
	s_cmp_eq_u32 s99, 0
	s_mul_hi_i32 s84, s72, 0x9000000
	v_lshl_add_u64 v[0:1], v[124:125], 0, s[74:75]
	s_cselect_b64 s[72:73], -1, 0
	s_add_u32 s74, s70, s85
	s_addc_u32 s75, s71, s84
	v_mov_b64_e32 v[2:3], s[74:75]
	v_mad_u64_u32 v[2:3], s[74:75], v0, s95, v[2:3]
	v_mad_i32_i24 v3, v1, s95, v3
	v_mov_b32_e32 v151, v173
	v_mov_b32_e32 v153, v172
	s_mov_b32 s76, 0
	s_mov_b32 s77, 0
	v_lshl_add_u64 v[162:163], v[142:143], 0, s[70:71]
	v_lshl_add_u64 v[164:165], v[148:149], 0, v[2:3]
	s_waitcnt vmcnt(6)
	v_mov_b64_e32 v[90:91], v[50:51]
	s_waitcnt vmcnt(5)
	v_mov_b64_e32 v[92:93], v[108:109]
	s_waitcnt vmcnt(4)
	v_mov_b64_e32 v[96:97], v[104:105]
	s_waitcnt vmcnt(3)
	v_mov_b64_e32 v[100:101], v[120:121]
	v_mov_b64_e32 v[88:89], v[48:49]
	v_mov_b64_e32 v[94:95], v[110:111]
	v_mov_b64_e32 v[98:99], v[106:107]
	v_mov_b64_e32 v[102:103], v[122:123]
	s_waitcnt vmcnt(2)
	v_mul_f32_e32 v155, 0x3fb8aa3b, v16
	s_branch .LBB0_315
